# P5/P6 chain stack on v52: 14-load GEMM prologues, seam-1 arrive deferred, hook prefetch, P6 last-iteration epilogue prefetch, final-norm weights requested before the exchange poll
# baseline (speedup 1.0000x reference)
; #define PG8_STAGE(bufoff, gbase, voff) do { _Pragma("unroll") for (int _i = 0; _i < 2; ++_i) \
;         __builtin_amdgcn_global_load_lds((const unsigned*)((const char*)(gbase) + (voff)[_i]), (PG8_LAS unsigned*)(lds + (bufoff) + ldsw + _i * 8192), 16, 0, 0); } while (0)
; #define PG8_WAIT_V(n) asm volatile("s_waitcnt vmcnt(" #n ")" ::: "memory")
; #define PG8_BAR __builtin_amdgcn_s_barrier()
; template <int ROT, class Epi0, class Epi1, class Late, class Post0>
; __device__ __forceinline__ void gemm_phase_pair(PG8_LAS unsigned char* lds, const Gemm g0, const Gemm g1, const Unit u, const Epi0& E0, const Epi1& E1, int wid_in, const Late& late, const Post0& post0) {
;     ...
;     const int aoff = lds_byte(wr * 64 + fr, fq * 8), boff = lds_byte(wc * 32 + fr, fq * 8);
;     f32x4 acc[2][2][4][2];
; #pragma unroll
;     for (int a = 0; a < 2; ++a)
; #pragma unroll
;         for (int b = 0; b < 2; ++b)
; #pragma unroll
;             for (int m = 0; m < 4; ++m)
; #pragma unroll
;                 for (int n = 0; n < 2; ++n) acc[a][b][m][n] = (f32x4){0.f, 0.f, 0.f, 0.f};
;     bf16x8 At[4][2], B0[2][2], B1[2][2];
;     const char* cA = (const char*)g0.A + (size_t)u.pm * 2 * hs0; const char* cB = (const char*)g0.Bt + (size_t)u.pn * 2 * hs0;
;     const char* nA = (const char*)g1.A + (size_t)u.pm * 2 * hs1; const char* nB = (const char*)g1.Bt + (size_t)u.pn * 2 * hs1;
;     ...
;     PG8_STAGE(PG8_SB(0, 0), cB + PG8_KT(0), vB0); PG8_STAGE(PG8_SB(0, 1), cB + hs0 + PG8_KT(0), vB0); PG8_STAGE(PG8_SA(0, 0), cA + PG8_KT(0), vA0); PG8_STAGE(PG8_SA(0, 1), cA + hs0 + PG8_KT(0), vA0);
;     if (wr == 1) PG8_BAR;
;     PG8_WAIT_V(2); PG8_BAR;
;     PG8_STAGE(PG8_SB(1, 0), cB + PG8_KT(1), vB0); PG8_STAGE(PG8_SA(1, 0), cA + PG8_KT(1), vA0); PG8_STAGE(PG8_SB(1, 1), cB + hs0 + PG8_KT(1), vB0);
;     PG8_WAIT_V(6); PG8_BAR;
.LBB0_846:
	v_readlane_b32 s7, v252, 5
	s_lshl_b32 s7, s7, 5
	s_and_b32 s52, s7, 0x60
	s_lshl_b32 s12, s6, 6
	v_ashrrev_i32_e32 v1, 6, v143
	s_lshr_b32 s7, s52, 3
	s_lshl_b32 s6, s6, 13
	v_lshl_add_u32 v12, v1, 10, s6
	v_add_lshl_u32 v1, v1, s7, 10
	s_mov_b64 s[6:7], 0x880
	s_add_i32 m0, s40, 0x18000
	v_lshl_add_u64 v[2:3], v[2:3], 0, s[6:7]
	global_load_lds_dwordx4 v[2:3], off
	v_lshl_add_u64 v[2:3], v[4:5], 0, s[6:7]
	s_add_i32 m0, s40, 0x1a000
	s_add_i32 s13, s40, 0x8000
	s_add_i32 s33, s40, 0xa000
	global_load_lds_dwordx4 v[2:3], off
	v_lshl_add_u64 v[2:3], v[6:7], 0, s[6:7]
	s_mov_b32 m0, s13
	s_add_u32 s4, s4, 0x80880
	global_load_lds_dwordx4 v[2:3], off
	v_lshl_add_u64 v[2:3], v[8:9], 0, s[6:7]
	s_mov_b32 m0, s33
	s_addc_u32 s5, s5, 0
	global_load_lds_dwordx4 v[2:3], off
	s_add_i32 m0, s40, 0x1c000
	v_lshl_add_u64 v[2:3], s[4:5], 0, v[132:133]
	global_load_lds_dwordx4 v[2:3], off
	v_lshl_add_u64 v[2:3], s[4:5], 0, v[130:131]
	s_add_i32 m0, s40, 0x1e000
	v_and_b32_e32 v136, 15, v143
	global_load_lds_dwordx4 v[2:3], off
	s_waitcnt vmcnt(8)
	s_barrier
	v_and_b32_e32 v10, 48, v143
	v_lshlrev_b32_e32 v11, 2, v143
	v_lshl_or_b32 v10, v136, 6, v10
	v_and_b32_e32 v11, 32, v11
	v_bitop3_b32 v1, v10, v1, v11 bitop3:0xde
	s_waitcnt vmcnt(6)
	s_add_i32 s49, 0, 0x10000
	s_add_i32 s48, 0, 0x14000
	s_add_i32 s44, 0, 0x18000
	s_add_i32 s43, 0, 0x1c000
	v_bitop3_b32 v10, v10, v12, v11 bitop3:0xde
	v_add_u32_e32 v141, s49, v1
	v_add_u32_e32 v140, s48, v1
	s_add_i32 s49, s49, s36
	s_add_i32 s48, s48, s36
	v_add_u32_e32 v139, s44, v1
	v_add_u32_e32 v138, s43, v1
	s_add_i32 s44, s44, s36
	s_add_i32 s43, s43, s36
	v_or_b32_e32 v142, s12, v136
	v_add_u32_e32 v137, 0, v10
	s_mov_b32 s53, -2
	s_mov_b64 s[4:5], 0x8c80880
	s_add_i32 s51, s40, 0xc000
	s_add_i32 s50, s40, 0xe000
	s_mov_b64 s[6:7], 0xd00900
	s_add_i32 s47, s49, 0x2000
	s_mov_b64 s[10:11], 0xd80900
	s_add_i32 s46, s48, 0x2000
	s_mov_b64 s[24:25], 0x8c00900
	s_mov_b64 s[26:27], 0x8c80900
	s_mov_b64 s[28:29], 0xd00980
	s_add_i32 s42, s44, 0x2000
	s_mov_b64 s[30:31], 0xd80980
	s_add_i32 s41, s43, 0x2000
	s_mov_b64 s[36:37], 0x8c00980
	s_mov_b64 s[38:39], s[96:97]
	v_mov_b32_e32 v134, v130
	v_mov_b32_e32 v130, v0
	v_mov_b32_e32 v0, v131
	v_mov_b32_e32 v1, v131
	v_mov_b32_e32 v2, v131
	v_mov_b32_e32 v3, v131
	v_mov_b32_e32 v4, v131
	v_mov_b32_e32 v5, v131
	v_mov_b32_e32 v6, v131
	v_mov_b32_e32 v7, v131
	v_mov_b32_e32 v8, v131
	v_mov_b32_e32 v9, v131
	v_mov_b32_e32 v10, v131
	v_mov_b32_e32 v11, v131
	v_mov_b32_e32 v12, v131
	v_mov_b32_e32 v13, v131
	v_mov_b32_e32 v14, v131
	v_mov_b32_e32 v15, v131
	v_mov_b32_e32 v16, v131
	v_mov_b32_e32 v17, v131
	v_mov_b32_e32 v18, v131
	v_mov_b32_e32 v19, v131
	v_mov_b32_e32 v20, v131
	v_mov_b32_e32 v21, v131
	v_mov_b32_e32 v22, v131
	v_mov_b32_e32 v23, v131
	v_mov_b32_e32 v24, v131
	v_mov_b32_e32 v25, v131
	v_mov_b32_e32 v26, v131
	v_mov_b32_e32 v27, v131
	v_mov_b32_e32 v28, v131
	v_mov_b32_e32 v29, v131
	v_mov_b32_e32 v30, v131
	v_mov_b32_e32 v31, v131
	v_mov_b32_e32 v32, v131
	v_mov_b32_e32 v33, v131
	v_mov_b32_e32 v34, v131
	v_mov_b32_e32 v35, v131
	v_mov_b32_e32 v36, v131
	v_mov_b32_e32 v37, v131
	v_mov_b32_e32 v38, v131
	v_mov_b32_e32 v39, v131
	v_mov_b32_e32 v40, v131
	v_mov_b32_e32 v41, v131
	v_mov_b32_e32 v42, v131
	v_mov_b32_e32 v43, v131
	v_mov_b32_e32 v44, v131
	v_mov_b32_e32 v45, v131
	v_mov_b32_e32 v46, v131
	v_mov_b32_e32 v47, v131
	v_mov_b32_e32 v48, v131
	v_mov_b32_e32 v49, v131
	v_mov_b32_e32 v50, v131
	v_mov_b32_e32 v51, v131
	v_mov_b32_e32 v52, v131
	v_mov_b32_e32 v53, v131
	v_mov_b32_e32 v54, v131
	v_mov_b32_e32 v55, v131
	v_mov_b32_e32 v56, v131
	v_mov_b32_e32 v57, v131
	v_mov_b32_e32 v58, v131
	v_mov_b32_e32 v59, v131
	v_mov_b32_e32 v60, v131
	v_mov_b32_e32 v61, v131
	v_mov_b32_e32 v62, v131
	v_mov_b32_e32 v63, v131
	v_mov_b32_e32 v64, v131
	v_mov_b32_e32 v65, v131
	v_mov_b32_e32 v66, v131
	v_mov_b32_e32 v67, v131
	v_mov_b32_e32 v68, v131
	v_mov_b32_e32 v69, v131
	v_mov_b32_e32 v70, v131
	v_mov_b32_e32 v71, v131
	v_mov_b32_e32 v72, v131
	v_mov_b32_e32 v73, v131
	v_mov_b32_e32 v74, v131
	v_mov_b32_e32 v75, v131
	v_mov_b32_e32 v76, v131
	v_mov_b32_e32 v77, v131
	v_mov_b32_e32 v78, v131
	v_mov_b32_e32 v79, v131
	v_mov_b32_e32 v80, v131
	v_mov_b32_e32 v81, v131
	v_mov_b32_e32 v82, v131
	v_mov_b32_e32 v83, v131
	v_mov_b32_e32 v84, v131
	v_mov_b32_e32 v85, v131
	v_mov_b32_e32 v86, v131
	v_mov_b32_e32 v87, v131
	v_mov_b32_e32 v88, v131
	v_mov_b32_e32 v89, v131
	v_mov_b32_e32 v90, v131
	v_mov_b32_e32 v91, v131
	v_mov_b32_e32 v92, v131
	v_mov_b32_e32 v93, v131
	v_mov_b32_e32 v94, v131
	v_mov_b32_e32 v95, v131
	v_mov_b32_e32 v96, v131
	v_mov_b32_e32 v97, v131
	v_mov_b32_e32 v98, v131
	v_mov_b32_e32 v99, v131
	v_mov_b32_e32 v100, v131
	v_mov_b32_e32 v101, v131
	v_mov_b32_e32 v102, v131
	v_mov_b32_e32 v103, v131
	v_mov_b32_e32 v104, v131
	v_mov_b32_e32 v105, v131
	v_mov_b32_e32 v106, v131
	v_mov_b32_e32 v107, v131
	v_mov_b32_e32 v108, v131
	v_mov_b32_e32 v109, v131
	v_mov_b32_e32 v110, v131
	v_mov_b32_e32 v111, v131
	v_mov_b32_e32 v112, v131
	v_mov_b32_e32 v113, v131
	v_mov_b32_e32 v114, v131
	v_mov_b32_e32 v115, v131
	v_mov_b32_e32 v116, v131
	v_mov_b32_e32 v117, v131
	v_mov_b32_e32 v118, v131
	v_mov_b32_e32 v119, v131
	v_mov_b32_e32 v120, v131
	v_mov_b32_e32 v121, v131
	v_mov_b32_e32 v122, v131
	v_mov_b32_e32 v123, v131
	v_mov_b32_e32 v124, v131
	v_mov_b32_e32 v125, v131
	v_mov_b32_e32 v126, v131
	v_mov_b32_e32 v127, v131
	s_barrier
	.p2align	6
	s_mov_b32 s98, 0
